# plus: grid barrier between gates phase and local scan removed: each workgroup scans the chunks and channels its own two gates tiles produced (index remap), workgroup barrier only
# speedup vs baseline: 1.0011x; 1.0011x over previous
;   DI float* carry() const { return (float*)(ws + OFF_CARRY); }
; DI int otid() { int t = threadIdx.x; asm volatile("" : "+v"(t)); return t; }
; DI void phase_scan_local(const Params& p) {
;   for (int i = blockIdx.x * NTH + otid(); i < NBATCH * 128 * 256; i += gridDim.x * NTH) {
;     const int ch = (i & 255) * 4, c = (i >> 8) & 127, b = i >> 15;
;     const size_t base = ((size_t)b * S + c * 32) * 1024 + ch;
;     f32x4 A = {1.f, 1.f, 1.f, 1.f}, H = {0.f, 0.f, 0.f, 0.f};
; #pragma unroll 1
;     for (int t0 = 0; t0 < 32; t0 += 8) {
;       f32x4 a[8], u[8];
; #pragma unroll
;       for (int j = 0; j < 8; ++j) { a[j] = *(const f32x4*)(p.av() + base + (size_t)(t0 + j) * 1024); u[j] = *(const f32x4*)(p.uv() + base + (size_t)(t0 + j) * 1024); }
; #pragma unroll
;       for (int j = 0; j < 8; ++j) { A *= a[j]; H = a[j] * H + u[j]; }
;     }
;     *(f32x4*)(p.carry() + (size_t)i * 4) = A; *(f32x4*)(p.carry() + (size_t)NBATCH * 128 * 1024 + (size_t)i * 4) = H;
.LBB0_568:
	s_waitcnt vmcnt(0)
	s_barrier
	s_and_b32 s0, s84, 63
	s_lshr_b32 s1, s0, 4
	s_lshl_b32 s1, s1, 15
	s_and_b32 s0, s0, 15
	s_lshl_b32 s0, s0, 11
	s_or_b32 s0, s0, s1
	s_lshr_b32 s1, s84, 6
	s_lshl_b32 s1, s1, 5
	s_or_b32 s0, s0, s1
	v_and_b32_e32 v0, 31, v206
	v_and_b32_e32 v1, 32, v206
	v_lshl_or_b32 v0, v1, 2, v0
	v_lshrrev_b32_e32 v1, 6, v206
	v_lshl_or_b32 v0, v1, 8, v0
	v_or_b32_e32 v8, s0, v0
	s_mov_b64 s[0:1], exec
	s_lshl_b32 s14, s96, 9
	s_add_u32 s2, s22, 0x14cc0000
	s_addc_u32 s3, s23, 0
	s_add_u32 s4, s22, 0x14ec0000
	s_addc_u32 s5, s23, 0
	s_add_u32 s8, s20, 0x4007000
	s_addc_u32 s9, s21, 0
	v_lshlrev_b32_e32 v12, 7, v8
	s_lshl_b32 s15, s96, 16
	v_lshlrev_b32_e32 v13, 2, v8
	s_lshl_b32 s16, s96, 11
	s_mov_b64 s[10:11], 0
	s_mov_b64 s[12:13], 0x8000
	s_mov_b32 s17, 0x1ffff
